# attention: cache-warm prefetch of merge lines (Y/GMA/CT/CARRY) at top-k start + hoisted merge loads + QK K-fragment prefetch
# speedup vs baseline: 1.0010x; 1.0010x over previous
; #define LAS __attribute__((address_space(3)))
; template <int DV>
; DI void attn_unit(const int wv, const Args& A, LAS unsigned char* lds, int b, int g, int qb, int dry) {
;     ...
;         const int qi2 = lane >> 3, l8 = lane & 7;
;         const LAS float* irow = IMP + (wave * 8 + qi2) * 132;
;         u64 slo = 0ull, shi = 0ull;
;         if (qb + 1 <= 16) { slo = (1ull << (qb + 1)) - 1ull; }
;         else {
;             float sc[16]; unsigned selm = 0u;
; #pragma unroll
;             for (int i = 0; i < 16; ++i) { const int jj = l8 + 8 * i; const bool forced = (jj == 0 || jj == qb || jj == qb - 1);
;                 const bool cand = (jj <= qb) && !forced; sc[i] = cand ? irow[jj] : -1.f; if (forced) selm |= 1u << i; }
.LBB0_834:
	v_lshrrev_b32_e32 v0, 3, v186
	v_and_b32_e32 v40, 7, v189
	s_waitcnt lgkmcnt(0)
	v_or_b32_e32 v3, s83, v0
	s_mov_b64 s[8:9], -1
	s_cmp_gt_u32 s93, 15
	v_cmp_eq_u32_e32 vcc, 0, v40
	s_waitcnt vmcnt(63) expcnt(7) lgkmcnt(15)
	s_barrier
	s_cbranch_scc0 .LBB0_870
	s_movk_i32 s8, 0x210
	v_mul_lo_u32 v0, v3, s8
	s_add_i32 s8, 0, 0x11800
	v_add_u32_e32 v1, s8, v0
	v_cmp_ne_u32_e64 s[8:9], 0, v40
	v_mov_b32_e32 v0, -1.0
	v_lshl_add_u32 v59, v40, 2, v1
	v_mov_b32_e32 v1, -1.0
	s_and_saveexec_b64 s[10:11], s[8:9]
	ds_read_b32 v1, v59
	s_or_b64 exec, exec, s[10:11]
	s_sub_i32 s26, 0x7e, s50
	v_or_b32_e32 v36, 8, v40
	v_cmp_ne_u32_e64 s[8:9], s26, v36
	v_mov_b32_e32 v58, 2
	s_and_saveexec_b64 s[10:11], s[8:9]
	ds_read_b32 v0, v59 offset:32
	v_mov_b32_e32 v58, 0
	s_or_b64 exec, exec, s[10:11]
	v_or_b32_e32 v37, 16, v40
	v_cmp_eq_u32_e64 s[8:9], s93, v37
	v_cmp_eq_u32_e64 s[10:11], s26, v37
	s_or_b64 s[70:71], s[8:9], s[10:11]
	s_xor_b64 s[10:11], s[70:71], -1
	v_cmp_ge_u32_e64 s[8:9], s93, v37
	s_and_b64 s[10:11], s[8:9], s[10:11]
	v_mov_b32_e32 v39, -1.0
	v_mov_b32_e32 v41, -1.0
	s_and_saveexec_b64 s[8:9], s[10:11]
	ds_read_b32 v41, v59 offset:64
	s_or_b64 exec, exec, s[8:9]
	v_or_b32_e32 v38, 24, v40
	v_cmp_eq_u32_e64 s[8:9], s93, v38
	v_cmp_eq_u32_e64 s[10:11], s26, v38
	s_or_b64 s[72:73], s[8:9], s[10:11]
	s_xor_b64 s[10:11], s[72:73], -1
	v_cmp_ge_u32_e64 s[8:9], s93, v38
	s_and_b64 s[10:11], s[8:9], s[10:11]
	s_and_saveexec_b64 s[8:9], s[10:11]
	ds_read_b32 v39, v59 offset:96
	s_or_b64 exec, exec, s[8:9]
	v_or_b32_e32 v42, 32, v40
	v_cmp_eq_u32_e64 s[8:9], s93, v42
	v_cmp_eq_u32_e64 s[10:11], s26, v42
	s_or_b64 s[74:75], s[8:9], s[10:11]
	s_xor_b64 s[10:11], s[74:75], -1
	v_cmp_ge_u32_e64 s[8:9], s93, v42
	s_and_b64 s[10:11], s[8:9], s[10:11]
	v_mov_b32_e32 v45, -1.0
	v_mov_b32_e32 v46, -1.0
	s_and_saveexec_b64 s[8:9], s[10:11]
	ds_read_b32 v46, v59 offset:128
	s_or_b64 exec, exec, s[8:9]
	v_or_b32_e32 v43, 40, v40
	v_cmp_eq_u32_e64 s[8:9], s93, v43
	v_cmp_eq_u32_e64 s[10:11], s26, v43
	s_or_b64 s[76:77], s[8:9], s[10:11]
	s_xor_b64 s[10:11], s[76:77], -1
	v_cmp_ge_u32_e64 s[8:9], s93, v43
	s_and_b64 s[10:11], s[8:9], s[10:11]
	s_and_saveexec_b64 s[8:9], s[10:11]
	ds_read_b32 v45, v59 offset:160
	s_or_b64 exec, exec, s[8:9]
	v_or_b32_e32 v44, 48, v40
	v_cmp_eq_u32_e64 s[8:9], s93, v44
	v_cmp_eq_u32_e64 s[10:11], s26, v44
	s_or_b64 s[78:79], s[8:9], s[10:11]
	s_xor_b64 s[10:11], s[78:79], -1
	v_cmp_ge_u32_e64 s[8:9], s93, v44
	s_and_b64 s[10:11], s[8:9], s[10:11]
	v_mov_b32_e32 v48, -1.0
	v_mov_b32_e32 v49, -1.0
	s_and_saveexec_b64 s[8:9], s[10:11]
	ds_read_b32 v49, v59 offset:192
	s_or_b64 exec, exec, s[8:9]
	v_or_b32_e32 v47, 56, v40
	v_cmp_eq_u32_e64 s[8:9], s93, v47
	v_cmp_eq_u32_e64 s[10:11], s26, v47
	s_or_b64 s[8:9], s[8:9], s[10:11]
	s_xor_b64 s[12:13], s[8:9], -1
	v_cmp_ge_u32_e64 s[10:11], s93, v47
	s_and_b64 s[12:13], s[10:11], s[12:13]
	s_and_saveexec_b64 s[10:11], s[12:13]
	ds_read_b32 v48, v59 offset:224
	s_or_b64 exec, exec, s[10:11]
	v_or_b32_e32 v50, 64, v40
	v_cmp_eq_u32_e64 s[10:11], s93, v50
	v_cmp_eq_u32_e64 s[12:13], s26, v50
	s_or_b64 s[10:11], s[10:11], s[12:13]
	s_xor_b64 s[14:15], s[10:11], -1
	v_cmp_ge_u32_e64 s[12:13], s93, v50
	s_and_b64 s[14:15], s[12:13], s[14:15]
	v_mov_b32_e32 v50, -1.0
	v_mov_b32_e32 v51, -1.0
	s_and_saveexec_b64 s[12:13], s[14:15]
	ds_read_b32 v51, v59 offset:256
	s_or_b64 exec, exec, s[12:13]
	v_or_b32_e32 v52, 0x48, v40
	v_cmp_eq_u32_e64 s[12:13], s93, v52
	v_cmp_eq_u32_e64 s[14:15], s26, v52
	s_or_b64 s[12:13], s[12:13], s[14:15]
	s_xor_b64 s[16:17], s[12:13], -1
	v_cmp_ge_u32_e64 s[14:15], s93, v52
	s_and_b64 s[16:17], s[14:15], s[16:17]
	s_and_saveexec_b64 s[14:15], s[16:17]
	ds_read_b32 v50, v59 offset:288
	s_or_b64 exec, exec, s[14:15]
	v_or_b32_e32 v52, 0x50, v40
	v_cmp_eq_u32_e64 s[14:15], s93, v52
	v_cmp_eq_u32_e64 s[16:17], s26, v52
	s_or_b64 s[14:15], s[14:15], s[16:17]
	s_xor_b64 s[18:19], s[14:15], -1
	v_cmp_ge_u32_e64 s[16:17], s93, v52
	s_and_b64 s[18:19], s[16:17], s[18:19]
	v_mov_b32_e32 v52, -1.0
	v_mov_b32_e32 v53, -1.0
	s_and_saveexec_b64 s[16:17], s[18:19]
	ds_read_b32 v53, v59 offset:320
	s_or_b64 exec, exec, s[16:17]
	v_or_b32_e32 v54, 0x58, v40
	v_cmp_eq_u32_e64 s[16:17], s93, v54
	v_cmp_eq_u32_e64 s[18:19], s26, v54
	s_or_b64 s[16:17], s[16:17], s[18:19]
	s_xor_b64 s[20:21], s[16:17], -1
	v_cmp_ge_u32_e64 s[18:19], s93, v54
	s_and_b64 s[20:21], s[18:19], s[20:21]
	s_and_saveexec_b64 s[18:19], s[20:21]
	ds_read_b32 v52, v59 offset:352
	s_or_b64 exec, exec, s[18:19]
	v_or_b32_e32 v54, 0x60, v40
	v_cmp_eq_u32_e64 s[18:19], s93, v54
	v_cmp_eq_u32_e64 s[20:21], s26, v54
	s_or_b64 s[18:19], s[18:19], s[20:21]
	s_xor_b64 s[22:23], s[18:19], -1
	v_cmp_ge_u32_e64 s[20:21], s93, v54
	s_and_b64 s[22:23], s[20:21], s[22:23]
	v_mov_b32_e32 v54, -1.0
	v_mov_b32_e32 v55, -1.0
	s_and_saveexec_b64 s[20:21], s[22:23]
	ds_read_b32 v55, v59 offset:384
	s_or_b64 exec, exec, s[20:21]
	v_or_b32_e32 v56, 0x68, v40
	v_cmp_eq_u32_e64 s[20:21], s93, v56
	v_cmp_eq_u32_e64 s[22:23], s26, v56
	s_or_b64 s[20:21], s[20:21], s[22:23]
	s_xor_b64 s[24:25], s[20:21], -1
	v_cmp_ge_u32_e64 s[22:23], s93, v56
	s_and_b64 s[24:25], s[22:23], s[24:25]
	s_and_saveexec_b64 s[22:23], s[24:25]
	ds_read_b32 v54, v59 offset:416
	s_or_b64 exec, exec, s[22:23]
	v_or_b32_e32 v56, 0x70, v40
	v_cmp_eq_u32_e64 s[22:23], s93, v56
	v_cmp_eq_u32_e64 s[24:25], s26, v56
	s_or_b64 s[22:23], s[22:23], s[24:25]
	s_xor_b64 s[58:59], s[22:23], -1
	v_cmp_ge_u32_e64 s[24:25], s93, v56
	s_and_b64 s[58:59], s[24:25], s[58:59]
	v_mov_b32_e32 v56, -1.0
	v_mov_b32_e32 v57, -1.0
	s_and_saveexec_b64 s[24:25], s[58:59]
	ds_read_b32 v57, v59 offset:448
	s_or_b64 exec, exec, s[24:25]
	v_or_b32_e32 v60, 0x78, v40
	v_cmp_eq_u32_e64 s[24:25], s93, v60
	v_cmp_eq_u32_e64 s[26:27], s26, v60
	s_or_b64 s[24:25], s[24:25], s[26:27]
	s_xor_b64 s[58:59], s[24:25], -1
	v_cmp_ge_u32_e64 s[26:27], s93, v60
	s_and_b64 s[58:59], s[26:27], s[58:59]
	s_and_saveexec_b64 s[26:27], s[58:59]
	ds_read_b32 v56, v59 offset:480
	s_or_b64 exec, exec, s[26:27]
	s_waitcnt vmcnt(0)
; template <int DV>
; DI void attn_unit(const int wv, const Args& A, LAS unsigned char* lds, int b, int g, int qb, int dry) {
;     ...
;             for (int i = 0; i < 16; ++i) { const int jj = l8 + 8 * i; const bool forced = (jj == 0 || jj == qb || jj == qb - 1);
;                 const bool cand = (jj <= qb) && !forced; sc[i] = cand ? irow[jj] : -1.f; if (forced) selm |= 1u << i; }
;     ...
;                 const size_t idx = tokrow * DM + head * 64 + mt * 32 + 8 * v + 4 * c.h;
;                 const u32x2 yr = *(const u32x2*)(Yb + idx), gm = *(const u32x2*)(GMA + idx), ct = *(const u32x2*)((const bf16*)(ws + WS_CT) + idx);
;                 const f32x4 cr = *(const f32x4*)((const float*)(ws + WS_CARRY) + ((size_t)b * 64 + (c.t >> 7)) * DM + head * 64 + mt * 32 + 8 * v + 4 * c.h);
	v_cndmask_b32_e64 v71, 0, 4, s[70:71]
	v_cndmask_b32_e64 v72, 0, 1, vcc
	v_cndmask_b32_e64 v69, 0, 16, s[74:75]
	v_cndmask_b32_e64 v70, 0, 8, s[72:73]
	v_or_b32_e32 v71, v71, v72
	v_cndmask_b32_e64 v67, 0, 64, s[78:79]
	v_cndmask_b32_e64 v68, 0, 32, s[76:77]
	v_or3_b32 v69, v71, v70, v69
	v_cndmask_b32_e64 v65, 0, v193, s[10:11]
	v_cndmask_b32_e64 v66, 0, v192, s[8:9]
	v_or3_b32 v67, v69, v68, v67
	v_cndmask_b32_e64 v63, 0, v195, s[14:15]
	v_cndmask_b32_e64 v64, 0, v194, s[12:13]
	v_or3_b32 v65, v67, v66, v65
	v_cndmask_b32_e64 v61, 0, v197, s[18:19]
	v_cndmask_b32_e64 v62, 0, v196, s[16:17]
	v_or3_b32 v63, v65, v64, v63
	v_cndmask_b32_e64 v59, 0, v199, s[22:23]
	v_cndmask_b32_e64 v60, 0, v198, s[20:21]
	v_or3_b32 v61, v63, v62, v61
	v_cndmask_b32_e64 v73, 0, v200, s[24:25]
	v_or3_b32 v59, v61, v60, v59
	v_or3_b32 v59, v59, v73, v58
	v_lshlrev_b32_e32 v233, 2, v208
	v_or3_b32 v232, v164, v211, v233
	v_lshlrev_b32_e32 v232, 1, v232
	v_lshlrev_b32_e32 v233, 4, v208
	v_lshl_add_u32 v233, v211, 2, v233
	s_lshl_b32 s98, s45, 18
	v_readlane_b32 s99, v254, 59
	s_nop 3
	s_add_u32 s98, s99, s98
	s_addc_u32 s99, s89, 0
	s_lshr_b32 s100, s91, 7
	s_lshl_b32 s100, s100, 12
	s_add_u32 s98, s98, s100
	s_addc_u32 s99, s99, 0
	v_readlane_b32 s100, v254, 2
	v_readlane_b32 s101, v254, 3
	global_load_dword v252, v232, s[64:65]
	global_load_dword v252, v232, s[66:67]
	global_load_dword v252, v233, s[98:99]
	global_load_dword v252, v233, s[98:99] offset:128
	s_nop 1
	global_load_dword v252, v232, s[100:101]
	s_mov_b32 s8, 13
